# v21 plus the two no-op zero adds of the attention steady-loop row sums replaced by s_nop (byte-neutral)
# baseline (speedup 1.0000x reference)
.LBB0_311:
	s_mov_b32 s37, s36
	s_mov_b32 s4, s33
	s_mov_b32 s1, s42
	v_add_u32_e32 v209, s5, v252
	ds_read_b64_tr_b16 v[216:217], v209 offset:24576
	ds_read_b64_tr_b16 v[218:219], v209 offset:25088
	v_add_f32_e32 v65, v96, v97
	v_add_f32_e32 v65, v98, v65
	v_add_f32_e32 v65, v99, v65
	v_add_f32_e32 v65, v100, v65
	v_add_f32_e32 v65, v101, v65
	v_cvt_pk_bf16_f32 v172, v96, v97
	v_cvt_pk_bf16_f32 v173, v98, v99
	s_waitcnt lgkmcnt(9)
	v_mfma_f32_32x32x16_bf16 v[128:143], v[204:207], v[156:159], v[230:245]
	ds_read_b64_tr_b16 v[204:205], v209 offset:28672
	ds_read_b64_tr_b16 v[206:207], v209 offset:29184
	v_add_f32_e32 v65, v102, v65
	v_add_f32_e32 v65, v103, v65
	v_add_f32_e32 v65, v104, v65
	v_add_f32_e32 v65, v105, v65
	v_cvt_pk_bf16_f32 v174, v100, v101
	v_cvt_pk_bf16_f32 v175, v102, v103
	s_waitcnt lgkmcnt(10)
	v_mfma_f32_32x32x16_bf16 v[112:127], v[200:203], v[156:159], v[230:245]
	ds_read_b64_tr_b16 v[74:75], v209 offset:25600
	ds_read_b64_tr_b16 v[76:77], v209 offset:26112
	v_add_f32_e32 v65, v106, v65
	v_add_f32_e32 v65, v107, v65
	v_add_f32_e32 v65, v108, v65
	v_add_f32_e32 v65, v109, v65
	v_cvt_pk_bf16_f32 v168, v104, v105
	v_cvt_pk_bf16_f32 v169, v106, v107
	s_waitcnt lgkmcnt(11)
	v_mfma_f32_32x32x16_bf16 v[128:143], v[196:199], v[152:155], v[128:143]
	ds_read_b64_tr_b16 v[70:71], v209 offset:29696
	ds_read_b64_tr_b16 v[72:73], v209 offset:30208
	v_add_f32_e32 v65, v110, v65
	v_add_f32_e32 v65, v111, v65
	v_add_f32_e32 v65, v80, v65
	v_add_f32_e32 v65, v81, v65
	v_cvt_pk_bf16_f32 v170, v108, v109
	v_cvt_pk_bf16_f32 v171, v110, v111
	s_waitcnt lgkmcnt(12)
	v_mfma_f32_32x32x16_bf16 v[112:127], v[192:195], v[152:155], v[112:127]
	ds_read_b64_tr_b16 v[66:67], v209 offset:26624
	ds_read_b64_tr_b16 v[68:69], v209 offset:27136
	v_add_f32_e32 v65, v82, v65
	v_add_f32_e32 v65, v83, v65
	v_add_f32_e32 v65, v84, v65
	v_add_f32_e32 v65, v85, v65
	v_cvt_pk_bf16_f32 v164, v80, v81
	v_cvt_pk_bf16_f32 v165, v82, v83
	s_waitcnt lgkmcnt(13)
	v_mfma_f32_32x32x16_bf16 v[128:143], v[188:191], v[148:151], v[128:143]
	ds_read_b64_tr_b16 v[100:101], v209 offset:30720
	ds_read_b64_tr_b16 v[102:103], v209 offset:31232
	v_add_f32_e32 v65, v86, v65
	v_add_f32_e32 v65, v87, v65
	v_add_f32_e32 v65, v88, v65
	v_add_f32_e32 v65, v89, v65
	v_cvt_pk_bf16_f32 v166, v84, v85
	v_cvt_pk_bf16_f32 v167, v86, v87
	s_waitcnt lgkmcnt(14)
	v_mfma_f32_32x32x16_bf16 v[112:127], v[184:187], v[148:151], v[112:127]
	ds_read_b64_tr_b16 v[96:97], v209 offset:27648
	ds_read_b64_tr_b16 v[98:99], v209 offset:28160
	v_add_f32_e32 v65, v90, v65
	v_add_f32_e32 v65, v91, v65
	v_add_f32_e32 v65, v92, v65
	v_add_f32_e32 v65, v93, v65
	v_cvt_pk_bf16_f32 v160, v88, v89
	v_cvt_pk_bf16_f32 v161, v90, v91
	s_waitcnt lgkmcnt(14)
	v_mfma_f32_32x32x16_bf16 v[128:143], v[180:183], v[144:147], v[128:143]
	ds_read_b64_tr_b16 v[86:87], v209 offset:31744
	ds_read_b64_tr_b16 v[88:89], v209 offset:32256
	v_add_f32_e32 v65, v94, v65
	v_add_f32_e32 v65, v95, v65
	s_nop 0
	v_cvt_pk_bf16_f32 v162, v92, v93
	v_cvt_pk_bf16_f32 v163, v94, v95
	v_mfma_f32_32x32x16_bf16 v[112:127], v[176:179], v[144:147], v[112:127]
	v_lshl_add_u64 v[190:191], v[212:213], 0, s[48:49]
	v_lshl_add_u64 v[78:79], v[190:191], 0, s[10:11]
	s_add_i32 s5, s42, s3
	s_mov_b32 m0, s5
	s_nop 0
	global_load_lds_dwordx4 v[78:79], off
	v_lshl_add_u64 v[188:189], v[210:211], 0, s[48:49]
	v_lshl_add_u64 v[78:79], v[188:189], 0, s[12:13]
	s_add_i32 s5, s36, s97
	s_mov_b32 m0, s5
	s_nop 0
	global_load_lds_dwordx4 v[78:79], off
	v_lshl_add_u64 v[78:79], v[188:189], 0, s[14:15]
	s_add_i32 s5, s36, s96
	s_mov_b32 m0, s5
	s_nop 0
	global_load_lds_dwordx4 v[78:79], off
	s_waitcnt lgkmcnt(14)
	v_mfma_f32_32x32x16_bf16 v[32:47], v[172:175], v[216:219], v[32:47]
	v_exp_f32_e32 v128, v128
	v_exp_f32_e32 v129, v129
	ds_read_b64_tr_b16 v[90:91], v209 offset:49152
	ds_read_b64_tr_b16 v[92:93], v209 offset:49664
	s_waitcnt lgkmcnt(14)
	v_mfma_f32_32x32x16_bf16 v[48:63], v[172:175], v[204:207], v[48:63]
	v_exp_f32_e32 v130, v130
	v_exp_f32_e32 v131, v131
	ds_read_b64_tr_b16 v[104:105], v209 offset:53248
	ds_read_b64_tr_b16 v[106:107], v209 offset:53760
	v_add_u32_e32 v94, s37, v250
	ds_read_b128 v[82:85], v94
	ds_read_b128 v[78:81], v94 offset:512
	s_waitcnt lgkmcnt(14)
	v_mfma_f32_32x32x16_bf16 v[32:47], v[168:171], v[74:77], v[32:47]
	v_exp_f32_e32 v132, v132
	v_exp_f32_e32 v133, v133
	ds_read_b64_tr_b16 v[108:109], v209 offset:50176
	ds_read_b64_tr_b16 v[110:111], v209 offset:50688
	ds_read_b128 v[184:187], v94 offset:2048
	ds_read_b128 v[176:179], v94 offset:2560
	v_mfma_f32_32x32x16_bf16 v[48:63], v[168:171], v[70:73], v[48:63]
	v_exp_f32_e32 v134, v134
	v_exp_f32_e32 v135, v135
	ds_read_b64_tr_b16 v[192:193], v209 offset:54272
	ds_read_b64_tr_b16 v[194:195], v209 offset:54784
	ds_read_b128 v[180:183], v94 offset:4096
	ds_read_b128 v[70:73], v94 offset:4608
	s_waitcnt lgkmcnt(14)
	v_mfma_f32_32x32x16_bf16 v[32:47], v[164:167], v[66:69], v[32:47]
	v_exp_f32_e32 v136, v136
	v_exp_f32_e32 v137, v137
	ds_read_b64_tr_b16 v[196:197], v209 offset:51200
	ds_read_b64_tr_b16 v[198:199], v209 offset:51712
	ds_read_b128 v[74:77], v94 offset:6144
	ds_read_b128 v[66:69], v94 offset:6656
	v_mfma_f32_32x32x16_bf16 v[48:63], v[164:167], v[100:103], v[48:63]
	v_exp_f32_e32 v138, v138
	v_exp_f32_e32 v139, v139
	ds_read_b64_tr_b16 v[100:101], v209 offset:55296
	ds_read_b64_tr_b16 v[102:103], v209 offset:55808
	v_mfma_f32_32x32x16_bf16 v[32:47], v[160:163], v[96:99], v[32:47]
	v_exp_f32_e32 v140, v140
	v_exp_f32_e32 v141, v141
	ds_read_b64_tr_b16 v[94:95], v209 offset:52224
	ds_read_b64_tr_b16 v[96:97], v209 offset:52736
	v_mfma_f32_32x32x16_bf16 v[48:63], v[160:163], v[86:89], v[48:63]
	v_exp_f32_e32 v142, v142
	v_exp_f32_e32 v143, v143
	ds_read_b64_tr_b16 v[86:87], v209 offset:56320
	ds_read_b64_tr_b16 v[88:89], v209 offset:56832
	s_waitcnt lgkmcnt(14)
	v_mfma_f32_32x32x16_bf16 v[0:15], v[172:175], v[90:93], v[0:15]
	v_exp_f32_e32 v112, v112
	v_exp_f32_e32 v113, v113
	v_mfma_f32_32x32x16_bf16 v[16:31], v[172:175], v[104:107], v[16:31]
	v_exp_f32_e32 v114, v114
	v_exp_f32_e32 v115, v115
	v_mfma_f32_32x32x16_bf16 v[0:15], v[168:171], v[108:111], v[0:15]
	v_exp_f32_e32 v116, v116
	v_exp_f32_e32 v117, v117
	s_waitcnt lgkmcnt(12)
	v_mfma_f32_32x32x16_bf16 v[16:31], v[168:171], v[192:195], v[16:31]
	v_exp_f32_e32 v118, v118
	v_exp_f32_e32 v119, v119
	s_waitcnt lgkmcnt(8)
	v_mfma_f32_32x32x16_bf16 v[0:15], v[164:167], v[196:199], v[0:15]
	v_exp_f32_e32 v120, v120
	v_exp_f32_e32 v121, v121
	s_waitcnt lgkmcnt(4)
	v_mfma_f32_32x32x16_bf16 v[16:31], v[164:167], v[100:103], v[16:31]
	v_exp_f32_e32 v122, v122
	v_exp_f32_e32 v123, v123
	s_waitcnt lgkmcnt(2)
	v_mfma_f32_32x32x16_bf16 v[0:15], v[160:163], v[94:97], v[0:15]
	v_exp_f32_e32 v124, v124
	v_exp_f32_e32 v125, v125
	s_waitcnt lgkmcnt(0)
	v_mfma_f32_32x32x16_bf16 v[16:31], v[160:163], v[86:89], v[16:31]
	v_exp_f32_e32 v126, v126
	v_exp_f32_e32 v127, v127
	s_waitcnt vmcnt(3) lgkmcnt(0)
	s_barrier
	s_add_i32 s5, s36, 0x2000
	s_cmpk_lg_i32 s36, 0x4000
	s_cselect_b32 s42, s5, 0
	v_add_u32_e32 v209, s1, v252
	ds_read_b64_tr_b16 v[192:193], v209 offset:24576
	ds_read_b64_tr_b16 v[194:195], v209 offset:25088
	v_mfma_f32_32x32x16_bf16 v[96:111], v[82:85], v[156:159], v[230:245]
	v_add_f32_e32 v86, v128, v129
	v_add_f32_e32 v86, v130, v86
	v_add_f32_e32 v86, v131, v86
	v_add_f32_e32 v86, v132, v86
	v_add_f32_e32 v86, v133, v86
	v_cvt_pk_bf16_f32 v172, v128, v129
	v_cvt_pk_bf16_f32 v173, v130, v131
	ds_read_b64_tr_b16 v[196:197], v209 offset:28672
	ds_read_b64_tr_b16 v[198:199], v209 offset:29184
	v_add_f32_e32 v82, v134, v86
	v_add_f32_e32 v82, v135, v82
	v_add_f32_e32 v82, v136, v82
	v_add_f32_e32 v128, v137, v82
	v_mfma_f32_32x32x16_bf16 v[80:95], v[78:81], v[156:159], v[230:245]
	v_cvt_pk_bf16_f32 v174, v132, v133
	v_cvt_pk_bf16_f32 v175, v134, v135
	ds_read_b64_tr_b16 v[216:217], v209 offset:25600
	ds_read_b64_tr_b16 v[218:219], v209 offset:26112
	v_mfma_f32_32x32x16_bf16 v[96:111], v[184:187], v[152:155], v[96:111]
	v_add_f32_e32 v78, v138, v128
	v_add_f32_e32 v78, v139, v78
	v_add_f32_e32 v78, v140, v78
	v_add_f32_e32 v78, v141, v78
	v_cvt_pk_bf16_f32 v168, v136, v137
	v_cvt_pk_bf16_f32 v169, v138, v139
	ds_read_b64_tr_b16 v[136:137], v209 offset:29696
	ds_read_b64_tr_b16 v[138:139], v209 offset:30208
	v_mfma_f32_32x32x16_bf16 v[80:95], v[176:179], v[152:155], v[80:95]
	v_add_f32_e32 v78, v142, v78
	v_add_f32_e32 v78, v143, v78
	v_add_f32_e32 v78, v112, v78
	v_add_f32_e32 v78, v113, v78
	v_cvt_pk_bf16_f32 v170, v140, v141
	v_cvt_pk_bf16_f32 v171, v142, v143
	ds_read_b64_tr_b16 v[132:133], v209 offset:26624
	ds_read_b64_tr_b16 v[134:135], v209 offset:27136
	v_mfma_f32_32x32x16_bf16 v[96:111], v[180:183], v[148:151], v[96:111]
	v_add_f32_e32 v78, v114, v78
	v_add_f32_e32 v78, v115, v78
	v_add_f32_e32 v78, v116, v78
	v_add_f32_e32 v78, v117, v78
	v_cvt_pk_bf16_f32 v164, v112, v113
	v_cvt_pk_bf16_f32 v165, v114, v115
	ds_read_b64_tr_b16 v[128:129], v209 offset:30720
	ds_read_b64_tr_b16 v[130:131], v209 offset:31232
	v_mfma_f32_32x32x16_bf16 v[80:95], v[70:73], v[148:151], v[80:95]
	v_add_f32_e32 v78, v118, v78
	v_add_f32_e32 v78, v119, v78
	v_add_f32_e32 v78, v120, v78
	v_add_f32_e32 v78, v121, v78
	v_cvt_pk_bf16_f32 v166, v116, v117
	v_cvt_pk_bf16_f32 v167, v118, v119
	ds_read_b64_tr_b16 v[112:113], v209 offset:27648
	ds_read_b64_tr_b16 v[114:115], v209 offset:28160
	v_mfma_f32_32x32x16_bf16 v[96:111], v[74:77], v[144:147], v[96:111]
	v_add_f32_e32 v70, v122, v78
	v_add_f32_e32 v70, v123, v70
	v_add_f32_e32 v70, v124, v70
	v_add_f32_e32 v78, v125, v70
	v_cvt_pk_bf16_f32 v160, v120, v121
	v_cvt_pk_bf16_f32 v161, v122, v123
	ds_read_b64_tr_b16 v[70:71], v209 offset:31744
	ds_read_b64_tr_b16 v[72:73], v209 offset:32256
	v_mfma_f32_32x32x16_bf16 v[80:95], v[66:69], v[144:147], v[80:95]
	v_add_f32_e32 v74, v126, v78
	v_add_f32_e32 v74, v127, v74
	s_nop 0
	v_cvt_pk_bf16_f32 v162, v124, v125
	v_cvt_pk_bf16_f32 v163, v126, v127
	v_lshl_add_u64 v[66:67], v[190:191], 0, s[16:17]
	s_add_i32 s1, s36, s3
	s_mov_b32 m0, s1
	s_nop 0
	global_load_lds_dwordx4 v[66:67], off
	v_lshl_add_u64 v[66:67], v[188:189], 0, s[18:19]
	s_add_i32 s1, s42, s97
	s_mov_b32 m0, s1
	s_nop 0
	global_load_lds_dwordx4 v[66:67], off
	v_lshl_add_u64 v[66:67], v[188:189], 0, s[20:21]
	s_add_i32 s1, s42, s96
	s_mov_b32 m0, s1
	s_nop 0
	global_load_lds_dwordx4 v[66:67], off
	s_waitcnt lgkmcnt(14)
	v_mfma_f32_32x32x16_bf16 v[32:47], v[172:175], v[192:195], v[32:47]
	v_exp_f32_e32 v96, v96
	v_exp_f32_e32 v97, v97
	ds_read_b64_tr_b16 v[66:67], v209 offset:49152
	ds_read_b64_tr_b16 v[68:69], v209 offset:49664
	s_waitcnt lgkmcnt(14)
	v_mfma_f32_32x32x16_bf16 v[48:63], v[172:175], v[196:199], v[48:63]
	v_exp_f32_e32 v98, v98
	v_exp_f32_e32 v99, v99
	ds_read_b64_tr_b16 v[76:77], v209 offset:53248
	ds_read_b64_tr_b16 v[78:79], v209 offset:53760
	v_add_u32_e32 v75, s42, v250
	ds_read_b128 v[204:207], v75
	ds_read_b128 v[200:203], v75 offset:512
	s_waitcnt lgkmcnt(14)
	v_mfma_f32_32x32x16_bf16 v[32:47], v[168:171], v[216:219], v[32:47]
	v_exp_f32_e32 v100, v100
	v_exp_f32_e32 v101, v101
	ds_read_b64_tr_b16 v[116:117], v209 offset:50176
	ds_read_b64_tr_b16 v[118:119], v209 offset:50688
	ds_read_b128 v[196:199], v75 offset:2048
	ds_read_b128 v[192:195], v75 offset:2560
	v_mfma_f32_32x32x16_bf16 v[48:63], v[168:171], v[136:139], v[48:63]
	v_exp_f32_e32 v102, v102
	v_exp_f32_e32 v103, v103
	ds_read_b64_tr_b16 v[120:121], v209 offset:54272
	ds_read_b64_tr_b16 v[122:123], v209 offset:54784
	ds_read_b128 v[188:191], v75 offset:4096
	ds_read_b128 v[184:187], v75 offset:4608
	s_waitcnt lgkmcnt(14)
	v_mfma_f32_32x32x16_bf16 v[32:47], v[164:167], v[132:135], v[32:47]
	v_exp_f32_e32 v104, v104
	v_exp_f32_e32 v105, v105
	ds_read_b64_tr_b16 v[124:125], v209 offset:51200
	ds_read_b64_tr_b16 v[126:127], v209 offset:51712
	ds_read_b128 v[180:183], v75 offset:6144
	ds_read_b128 v[176:179], v75 offset:6656
	v_mfma_f32_32x32x16_bf16 v[48:63], v[164:167], v[128:131], v[48:63]
	v_exp_f32_e32 v106, v106
	v_exp_f32_e32 v107, v107
	ds_read_b64_tr_b16 v[128:129], v209 offset:55296
	ds_read_b64_tr_b16 v[130:131], v209 offset:55808
	v_mfma_f32_32x32x16_bf16 v[32:47], v[160:163], v[112:115], v[32:47]
	v_exp_f32_e32 v108, v108
	v_exp_f32_e32 v109, v109
	ds_read_b64_tr_b16 v[112:113], v209 offset:52224
	ds_read_b64_tr_b16 v[114:115], v209 offset:52736
	v_mfma_f32_32x32x16_bf16 v[48:63], v[160:163], v[70:73], v[48:63]
	v_exp_f32_e32 v110, v110
	v_exp_f32_e32 v111, v111
	ds_read_b64_tr_b16 v[70:71], v209 offset:56320
	ds_read_b64_tr_b16 v[72:73], v209 offset:56832
	s_waitcnt lgkmcnt(14)
	v_mfma_f32_32x32x16_bf16 v[0:15], v[172:175], v[66:69], v[0:15]
	v_exp_f32_e32 v80, v80
	v_exp_f32_e32 v81, v81
	v_mfma_f32_32x32x16_bf16 v[16:31], v[172:175], v[76:79], v[16:31]
	v_exp_f32_e32 v82, v82
	v_exp_f32_e32 v83, v83
	v_mfma_f32_32x32x16_bf16 v[0:15], v[168:171], v[116:119], v[0:15]
	v_exp_f32_e32 v84, v84
	v_exp_f32_e32 v85, v85
	s_waitcnt lgkmcnt(12)
	v_mfma_f32_32x32x16_bf16 v[16:31], v[168:171], v[120:123], v[16:31]
	v_exp_f32_e32 v86, v86
	v_exp_f32_e32 v87, v87
	s_waitcnt lgkmcnt(8)
	v_mfma_f32_32x32x16_bf16 v[0:15], v[164:167], v[124:127], v[0:15]
	v_exp_f32_e32 v88, v88
	v_exp_f32_e32 v89, v89
	s_waitcnt lgkmcnt(4)
	v_mfma_f32_32x32x16_bf16 v[16:31], v[164:167], v[128:131], v[16:31]
	v_exp_f32_e32 v90, v90
	v_exp_f32_e32 v91, v91
	s_waitcnt lgkmcnt(2)
	v_mfma_f32_32x32x16_bf16 v[0:15], v[160:163], v[112:115], v[0:15]
	v_exp_f32_e32 v92, v92
	v_exp_f32_e32 v93, v93
	s_waitcnt lgkmcnt(0)
	v_mfma_f32_32x32x16_bf16 v[16:31], v[160:163], v[70:73], v[16:31]
	v_exp_f32_e32 v94, v94
	v_exp_f32_e32 v95, v95
	s_add_i32 s1, s42, 0x2000
	s_waitcnt vmcnt(3) lgkmcnt(0)
	s_barrier
; #define WAIT_BAR(N) asm volatile("s_waitcnt vmcnt(" #N ") lgkmcnt(0)\n\ts_barrier":::"memory")
;   #define RESC() do{ if(resc){ asm volatile("s_waitcnt lgkmcnt(0)":::"memory"); \
;       _Pragma("unroll") for(int d_=0;d_<2;++d_) _Pragma("unroll") for(int r=0;r<16;++r){const float f_=wsf[crow(r,hi)];o[d_][r]*=f_;o2[d_][r]*=f_;} } }while(0)
;   #define ROT() do{sl_prev=sl_cur;sl_cur=sl_next;sl_next=(sl_next==(NSLOT-1)*SLOTB)?0:sl_next+SLOTB;}while(0)
; template<int THRL> __device__ __forceinline__ void attn_unit(int b,int h,int qb,unsigned char*wsb,char*shm,float kmax,const int CMB,float lam){
;     ...
;   for(;t+5<NT;t+=2){
;     STEP(pB0,pB1,pA0,pA1,t,true,true,true);     WAIT_BAR(3); RESC(); ROT();
;     STEP(pA0,pA1,pB0,pB1,t+1,true,true,true);   WAIT_BAR(3); RESC(); ROT();
;   }
	s_cmpk_lg_i32 s42, 0x4000
	v_add_f32_e32 v64, v64, v65
	s_mov_b32 s5, s36
	s_cselect_b32 s36, s1, 0
	s_add_i32 s33, s33, 2
	v_lshl_add_u64 v[210:211], v[210:211], 0, s[22:23]
	v_lshl_add_u64 v[212:213], v[212:213], 0, s[22:23]
	s_cmp_ge_u32 s33, s89
	v_add_f32_e32 v64, v64, v74
	s_cbranch_scc0 .LBB0_311
	ds_read_b32 v230, v246
	ds_read_b32 v231, v246 offset:2048
	ds_read_b32 v232, v246 offset:4096
	ds_read_b32 v233, v246 offset:6144
	ds_read_b32 v234, v246 offset:8192
	ds_read_b32 v235, v246 offset:10240
	ds_read_b32 v236, v246 offset:12288
	ds_read_b32 v237, v246 offset:14336
	ds_read_b32 v238, v246 offset:16384
	ds_read_b32 v239, v246 offset:18432
	ds_read_b32 v240, v246 offset:20480
	ds_read_b32 v241, v246 offset:22528
	ds_read_b32 v242, v246 offset:24576
	ds_read_b32 v243, v246 offset:26624
	ds_read_b32 v244, v246 offset:28672
	ds_read_b32 v245, v246 offset:30720
	ds_read_b32 v246, v246 offset:32768
	s_waitcnt lgkmcnt(0)
	s_nop 0
	s_nop 0
	s_nop 0
	s_nop 0
	s_nop 0
	s_nop 0
	s_nop 0
	s_nop 0
	s_nop 0
	s_nop 0
	s_nop 0
	s_nop 0
	s_nop 0
	s_nop 0
	s_nop 0
	s_nop 0
	s_nop 0
	s_nop 0
	s_nop 0
	s_nop 0
	s_nop 0
	s_nop 0
	s_nop 0
	s_nop 0
	s_add_i32 s6, s4, -3
	s_branch .LBB0_314
